# nt hint on the G1 epilogue stores on top of v111
# baseline (speedup 1.0000x reference)
; __device__ __forceinline__ unsigned cvt_pk_bf16(float lo, float hi) { unsigned r; asm volatile("v_cvt_pk_bf16_f32 %0, %1, %2" : "=v"(r) : "v"(lo), "v"(hi)); return r; }
; #define PG8_BAR __builtin_amdgcn_s_barrier()
;     __device__ __forceinline__ void operator()(const f32x4 (&acc)[2][2][4][2], const Unit& u, int wr, int wc, int fr, int fq) const {
;         const int row0 = u.pm * BM + wr * 64 + fr; const int col0 = u.pn * BM + wc * 32 + 8 * fq;
; #pragma unroll
;         for (int ai = 0; ai < 2; ++ai)
; #pragma unroll
;             for (int m = 0; m < 4; ++m) { bf16_t* rowp = O + (size_t)(row0 + ai * HALF + m * 16) * ldc + col0;
; #pragma unroll
;                 for (int bj = 0; bj < 2; ++bj) { const f32x4 v0 = acc[ai][bj][m][0], v1 = acc[ai][bj][m][1];
;                     u32x4 w; w.x = cvt_pk_bf16(v0[0], v0[1]); w.y = cvt_pk_bf16(v0[2], v0[3]); w.z = cvt_pk_bf16(v1[0], v1[1]); w.w = cvt_pk_bf16(v1[2], v1[3]);
;                     *(u32x4*)(rowp + bj * HALF) = w; } }
; template <class Epi, class Sched, bool ALIGN_EPI = false, bool SP2 = false>
; __device__ __forceinline__ void gemm_phase(PG8_LAS unsigned char* lds, const Gemm g, const Sched& S, const Epi& E) {
;     ...
;         if constexpr (ALIGN_EPI) { if (wr == 0) PG8_BAR; }
;         if constexpr (!Epi::AFTER_DRAIN) { E(acc, cur, wr, wc, fr, fq); S.done(cur); }
;         if (!has_next) break;
; #pragma unroll
;         for (int a = 0; a < 2; ++a)
; #pragma unroll
;             for (int b = 0; b < 2; ++b)
; #pragma unroll
;                 for (int m = 0; m < 4; ++m)
; #pragma unroll
;                     for (int n = 0; n < 2; ++n) acc[a][b][m][n] = (f32x4){0.f, 0.f, 0.f, 0.f};
;         cur = nxt; cA = nA; cB = nB; ++ui;
;         if constexpr (ALIGN_EPI) { if (wr == 1) PG8_BAR; }
.LBB0_188:
	v_mbcnt_lo_u32_b32 v186, -1, 0
	v_mbcnt_hi_u32_b32 v186, -1, v186
	v_and_b32_e32 v189, 64, v150
	v_and_b32_e32 v190, 0x60, v152
	v_lshrrev_b32_e32 v187, 2, v186
	v_and_b32_e32 v188, 3, v186
	v_mul_u32_u24_e32 v193, 0xc0, v189
	v_mul_u32_u24_e32 v191, 0x60, v190
	v_add_u32_e32 v193, v193, v191
	v_add_u32_e32 v193, 0x20000, v193
	v_and_b32_e32 v191, 15, v186
	v_mul_u32_u24_e32 v191, 0x90, v191
	v_lshrrev_b32_e32 v192, 4, v186
	v_lshl_add_u32 v191, v192, 4, v191
	v_add_u32_e32 v194, v193, v191
	v_mul_u32_u24_e32 v191, 0x90, v187
	v_lshl_add_u32 v191, v188, 4, v191
	v_add_u32_e32 v195, v193, v191
	v_add_u32_e32 v191, v189, v187
	v_lshl_add_u32 v191, s35, 8, v191
	v_lshl_add_u32 v192, v188, 3, v190
	v_lshl_or_b32 v192, s34, 8, v192
	v_mul_u32_u24_e32 v191, 0x1200, v191
	v_lshl_add_u32 v196, v192, 1, v191
	v_add_u32_e32 v197, 0x12000, v196
	v_add_u32_e32 v198, 0x24000, v196
	v_add_u32_e32 v199, 0x36000, v196
	v_add_u32_e32 v200, 0x90000, v196
	v_add_u32_e32 v201, 0xa2000, v196
	v_add_u32_e32 v202, 0xb4000, v196
	v_add_u32_e32 v203, 0xc6000, v196
	v_cvt_pk_bf16_f32 v134, v134, v135
	v_cvt_pk_bf16_f32 v135, v136, v137
	v_cvt_pk_bf16_f32 v136, v130, v131
	v_cvt_pk_bf16_f32 v137, v132, v133
	ds_write_b128 v194, v[134:137]
	ds_read_b128 v[134:137], v195
	v_cvt_pk_bf16_f32 v122, v122, v123
	v_cvt_pk_bf16_f32 v123, v124, v125
	v_cvt_pk_bf16_f32 v124, v114, v115
	v_cvt_pk_bf16_f32 v125, v116, v117
	ds_write_b128 v194, v[122:125]
	ds_read_b128 v[122:125], v195
	s_waitcnt lgkmcnt(2)
	global_store_dwordx4 v196, v[134:137], s[92:93] nt
	v_cvt_pk_bf16_f32 v114, v126, v127
	v_cvt_pk_bf16_f32 v115, v128, v129
	v_cvt_pk_bf16_f32 v116, v118, v119
	v_cvt_pk_bf16_f32 v117, v120, v121
	ds_write_b128 v194, v[114:117]
	ds_read_b128 v[114:117], v195
	s_waitcnt lgkmcnt(2)
	global_store_dwordx4 v196, v[122:125], s[92:93] offset:256 nt
	v_cvt_pk_bf16_f32 v106, v106, v107
	v_cvt_pk_bf16_f32 v107, v108, v109
	v_cvt_pk_bf16_f32 v108, v98, v99
	v_cvt_pk_bf16_f32 v109, v100, v101
	ds_write_b128 v194, v[106:109]
	ds_read_b128 v[106:109], v195
	s_waitcnt lgkmcnt(2)
	global_store_dwordx4 v197, v[114:117], s[92:93] nt
	v_cvt_pk_bf16_f32 v98, v110, v111
	v_cvt_pk_bf16_f32 v99, v112, v113
	v_cvt_pk_bf16_f32 v100, v102, v103
	v_cvt_pk_bf16_f32 v101, v104, v105
	ds_write_b128 v194, v[98:101]
	ds_read_b128 v[98:101], v195
	s_waitcnt lgkmcnt(2)
	global_store_dwordx4 v197, v[106:109], s[92:93] offset:256 nt
	v_cvt_pk_bf16_f32 v90, v90, v91
	v_cvt_pk_bf16_f32 v91, v92, v93
	v_cvt_pk_bf16_f32 v92, v82, v83
	v_cvt_pk_bf16_f32 v93, v84, v85
	ds_write_b128 v194, v[90:93]
	ds_read_b128 v[90:93], v195
	s_waitcnt lgkmcnt(2)
	global_store_dwordx4 v198, v[98:101], s[92:93] nt
	v_cvt_pk_bf16_f32 v82, v94, v95
	v_cvt_pk_bf16_f32 v83, v96, v97
	v_cvt_pk_bf16_f32 v84, v86, v87
	v_cvt_pk_bf16_f32 v85, v88, v89
	ds_write_b128 v194, v[82:85]
	ds_read_b128 v[82:85], v195
	s_waitcnt lgkmcnt(2)
	global_store_dwordx4 v198, v[90:93], s[92:93] offset:256 nt
	v_cvt_pk_bf16_f32 v78, v78, v79
	v_cvt_pk_bf16_f32 v79, v80, v81
	v_cvt_pk_bf16_f32 v80, v74, v75
	v_cvt_pk_bf16_f32 v81, v76, v77
	ds_write_b128 v194, v[78:81]
	ds_read_b128 v[78:81], v195
	s_waitcnt lgkmcnt(2)
	global_store_dwordx4 v199, v[82:85], s[92:93] nt
	v_cvt_pk_bf16_f32 v70, v70, v71
	v_cvt_pk_bf16_f32 v71, v72, v73
	v_cvt_pk_bf16_f32 v72, v66, v67
	v_cvt_pk_bf16_f32 v73, v68, v69
	ds_write_b128 v194, v[70:73]
	ds_read_b128 v[70:73], v195
	s_waitcnt lgkmcnt(2)
	global_store_dwordx4 v199, v[78:81], s[92:93] offset:256 nt
	v_cvt_pk_bf16_f32 v58, v58, v59
	v_cvt_pk_bf16_f32 v59, v60, v61
	v_cvt_pk_bf16_f32 v60, v50, v51
	v_cvt_pk_bf16_f32 v61, v52, v53
	ds_write_b128 v194, v[58:61]
	ds_read_b128 v[58:61], v195
	s_waitcnt lgkmcnt(2)
	global_store_dwordx4 v200, v[70:73], s[92:93] nt
	v_cvt_pk_bf16_f32 v50, v62, v63
	v_cvt_pk_bf16_f32 v51, v64, v65
	v_cvt_pk_bf16_f32 v52, v54, v55
	v_cvt_pk_bf16_f32 v53, v56, v57
	ds_write_b128 v194, v[50:53]
	ds_read_b128 v[50:53], v195
	s_waitcnt lgkmcnt(2)
	global_store_dwordx4 v200, v[58:61], s[92:93] offset:256 nt
	v_cvt_pk_bf16_f32 v42, v42, v43
	v_cvt_pk_bf16_f32 v43, v44, v45
	v_cvt_pk_bf16_f32 v44, v26, v27
	v_cvt_pk_bf16_f32 v45, v28, v29
	ds_write_b128 v194, v[42:45]
	ds_read_b128 v[42:45], v195
	s_waitcnt lgkmcnt(2)
	global_store_dwordx4 v201, v[50:53], s[92:93] nt
	v_cvt_pk_bf16_f32 v26, v46, v47
	v_cvt_pk_bf16_f32 v27, v48, v49
	v_cvt_pk_bf16_f32 v28, v30, v31
	v_cvt_pk_bf16_f32 v29, v32, v33
	ds_write_b128 v194, v[26:29]
	ds_read_b128 v[26:29], v195
	s_waitcnt lgkmcnt(2)
	global_store_dwordx4 v201, v[42:45], s[92:93] offset:256 nt
	v_cvt_pk_bf16_f32 v18, v18, v19
	v_cvt_pk_bf16_f32 v19, v20, v21
	v_cvt_pk_bf16_f32 v20, v10, v11
	v_cvt_pk_bf16_f32 v21, v12, v13
	ds_write_b128 v194, v[18:21]
	ds_read_b128 v[18:21], v195
	s_waitcnt lgkmcnt(2)
	global_store_dwordx4 v202, v[26:29], s[92:93] nt
	v_cvt_pk_bf16_f32 v10, v22, v23
	v_cvt_pk_bf16_f32 v11, v24, v25
	v_cvt_pk_bf16_f32 v12, v14, v15
	v_cvt_pk_bf16_f32 v13, v16, v17
	ds_write_b128 v194, v[10:13]
	ds_read_b128 v[10:13], v195
	s_waitcnt lgkmcnt(2)
	global_store_dwordx4 v202, v[18:21], s[92:93] offset:256 nt
	v_cvt_pk_bf16_f32 v6, v6, v7
	v_cvt_pk_bf16_f32 v7, v8, v9
	v_cvt_pk_bf16_f32 v8, v2, v3
	v_cvt_pk_bf16_f32 v9, v4, v5
	ds_write_b128 v194, v[6:9]
	ds_read_b128 v[6:9], v195
	s_waitcnt lgkmcnt(2)
	global_store_dwordx4 v203, v[10:13], s[92:93] nt
	s_waitcnt lgkmcnt(0)
	global_store_dwordx4 v203, v[6:9], s[92:93] offset:256 nt
	s_andn2_b64 vcc, exec, s[0:1]
	s_mov_b64 s[0:1], -1
	s_cbranch_vccnz .LBB0_177
	s_andn2_b64 vcc, exec, s[2:3]
	s_cbranch_vccnz .LBB0_176
	s_barrier
	s_branch .LBB0_176
